# grid seam: L1 invalidate issued by wave 1 at arrival (overlaps thread 0 arrive/poll) instead of after the poll succeeds
# speedup vs baseline: 1.0147x; 1.0147x over previous
.LBB0_1089:
	v_readlane_b32 s0, v254, 2
	v_readlane_b32 s1, v254, 3
	s_and_b64 vcc, exec, s[0:1]
	s_cbranch_vccz .LBB0_1202
	s_waitcnt vmcnt(0)
	s_waitcnt vmcnt(0)
	s_barrier
	v_readfirstlane_b32 s99, v244
	s_lshr_b32 s99, s99, 6
	s_cmp_lg_u32 s99, 1
	s_cbranch_scc1 .Lei_skip
	buffer_inv sc1
	s_waitcnt vmcnt(0)
.Lei_skip:
	s_and_saveexec_b64 s[0:1], s[22:23]
	s_cbranch_execz .LBB0_1168
	v_readlane_b32 s2, v254, 11
	s_waitcnt vmcnt(0) expcnt(0) lgkmcnt(0)
	s_nop 0
	v_mov_b32_e32 v0, s2
	ds_read_b32 v2, v0
	v_readlane_b32 s2, v254, 12
	s_waitcnt lgkmcnt(0)
	v_cmp_ne_u32_e32 vcc, 0, v2
	v_mov_b32_e32 v0, s2
	ds_read_b32 v0, v0
	s_cbranch_vccnz .LBB0_1105
	s_mov_b32 s7, 0
	s_branch .LBB0_1094

.LBB0_1167:
	s_waitcnt vmcnt(0)
	s_waitcnt vmcnt(0)
